# in-projection column-tile relabelling through a 22-entry annealed table instead of the affine map
# baseline (speedup 1.0000x reference)
.LBB0_241:
	s_andn2_b64 vcc, exec, s[0:1]
	s_cbranch_vccnz .LBB0_243
	s_and_b32 s0, s58, 0xffff
	s_mul_i32 s0, s0, 0xba2f
	s_lshr_b32 s0, s0, 23
	s_mul_i32 s1, s0, 0xb0
	s_sub_i32 s1, s58, s1
	s_bfe_u32 s42, s1, 0xd0003
	s_lshl_b32 s0, s0, 3
	s_and_b32 s1, s1, 7
	s_or_b32 s18, s1, s0
	s_mov_b32 s2, 0x52e41cb1
	s_mov_b32 s3, 0x62db30d
	s_mov_b32 s16, 0x1012866
	s_mov_b32 s17, 0x2447d
	s_sub_u32 s1, s42, 12
	s_cmp_lt_u32 s42, 12
	s_cselect_b32 s1, s42, s1
	s_cselect_b64 s[2:3], s[2:3], s[16:17]
	s_mul_i32 s1, s1, 5
	s_lshr_b64 s[2:3], s[2:3], s1
	s_and_b32 s42, s2, 31
